# acc-paired MFMA order in all GEMM loops + P4 walks its rounds in reverse (MALL reuse of XB from P3 and of HID by P5)
# speedup vs baseline: 1.0077x; 1.0077x over previous
; #define PG8_STAGE(bufoff, gbase, voff) do { _Pragma("unroll") for (int _i = 0; _i < 2; ++_i) \
;         __builtin_amdgcn_global_load_lds((const unsigned*)((const char*)(gbase) + (voff)[_i]), (LAS unsigned*)(lds + (bufoff) + ldsw + _i * 8192), 16, 0, 0); } while (0)
; #define PG8_WAIT_V(n) asm volatile("s_waitcnt vmcnt(" #n ")" ::: "memory")
; #define PG8_BAR __builtin_amdgcn_s_barrier()
;     __device__ bool next(int i, Unit& u) const {
;         if (rev && i >= rev) return false;
;         const long L = (long)(rev ? rev - 1 - i : i) * G + c; if (L >= nwg) return false;
;         int wgid = (int)L; { const int q = nwg / NXCD, r = nwg % NXCD, xcd = wgid % NXCD, off = wgid / NXCD; wgid = (xcd < r ? xcd * (q + 1) : r * (q + 1) + (xcd - r) * q) + off; }
;         const int nig = WGM * nN, gid = wgid / nig, fm = gid * WGM, gsz = (nM - fm) < WGM ? (nM - fm) : WGM;
;         u.pm = fm + ((wgid % nig) % gsz); u.pn = (wgid % nig) / gsz; return true;
; template <class Epi, class Ptrs>
; __device__ __forceinline__ void gemm_phase(LAS unsigned char* lds, const int K, const StaticOrder& S, const Ptrs& P, const Epi& E) {
;     ...
;     PG8_STAGE(PG8_SB(0, 0), cB, voffB); PG8_STAGE(PG8_SA(0, 0), cA, voffA); PG8_STAGE(PG8_SB(0, 1), cB + hstep, voffB); PG8_STAGE(PG8_SA(0, 1), cA + hstep, voffA);
;     if (wr == 1) PG8_BAR;
;     PG8_WAIT_V(4); PG8_BAR;
.LBB0_423:
	s_cmp_lt_i32 s30, 5
	s_cselect_b64 s[4:5], -1, 0
	s_and_b64 s[6:7], s[4:5], s[0:1]
	s_andn2_b64 vcc, exec, s[6:7]
	s_cbranch_vccnz .LBB0_438
	s_cmpk_gt_i32 s2, 0x17ff
	v_readfirstlane_b32 s46, v208
	s_cbranch_scc1 .LBB0_438
	v_lshrrev_b32_e32 v2, 1, v208
	v_and_b32_e32 v11, 24, v2
	v_lshrrev_b32_e32 v2, 5, v208
	v_and_b32_e32 v2, 4, v2
	v_bfe_u32 v3, v208, 2, 2
	s_add_u32 s47, s28, 0x2000000
	v_lshlrev_b32_e32 v0, 4, v208
	v_and_b32_e32 v1, 32, v208
	v_bfe_u32 v10, v208, 2, 4
	v_or3_b32 v2, v2, v3, v11
	v_lshrrev_b32_e32 v3, 3, v208
	s_movk_i32 s0, 0x70
	s_addc_u32 s48, s29, 0
	v_bitop3_b32 v8, v0, v1, 48 bitop3:0x6c
	v_and_b32_e32 v9, 64, v208
	v_and_or_b32 v4, v3, s0, v10
	s_movk_i32 s0, 0x60
	v_add_u32_e32 v12, 0x2000, v0
	s_add_u32 s49, s28, 0xe00000
	v_or_b32_e32 v1, v8, v9
	v_and_or_b32 v3, v3, s0, v2
	v_lshrrev_b32_e32 v0, 7, v12
	s_movk_i32 s0, 0xf0
	s_addc_u32 s50, s29, 0
	v_lshl_or_b32 v130, v3, 11, v1
	v_and_or_b32 v3, v0, s0, v10
	s_movk_i32 s0, 0xe0
	s_cmpk_eq_i32 s3, 0x100
	s_cselect_b32 s75, 0x1700, 0
	s_add_i32 s75, s75, s2
	s_ashr_i32 s54, s2, 31
	v_and_or_b32 v0, v0, s0, v2
	s_lshr_b32 s0, s54, 29
	s_add_i32 s0, s75, s0
	s_lshr_b32 s4, s46, 6
	s_ashr_i32 s5, s0, 3
	s_and_b32 s0, s0, -8
	s_lshr_b32 s1, s46, 8
	s_lshl_b32 s51, s4, 10
	s_sub_i32 s0, s75, s0
	s_cmp_lt_i32 s0, 0
	s_movk_i32 s55, 0x301
	s_cselect_b32 s10, s55, 0x300
	s_mul_i32 s0, s0, s10
	s_add_i32 s0, s0, s5
	s_ashr_i32 s5, s0, 31
	s_lshr_b32 s5, s5, 25
	s_add_i32 s5, s0, s5
	s_ashr_i32 s10, s5, 7
	s_and_b32 s5, s5, 0xff80
	s_sub_i32 s0, s0, s5
	s_bfe_i32 s5, s0, 0x80000
	s_bfe_u32 s5, s5, 0x3000c
	s_add_i32 s5, s0, s5
	s_and_b32 s11, s5, 0xf8
	s_sub_i32 s0, s0, s11
	s_lshl_b32 s10, s10, 3
	s_sext_i32_i8 s0, s0
	s_add_i32 s38, s10, s0
	s_bfe_i32 s0, s5, 0x80000
	s_sext_i32_i16 s0, s0
	s_lshr_b32 s0, s0, 3
	s_ashr_i32 s39, s38, 31
	s_bfe_i64 s[12:13], s[0:1], 0x100000
	s_lshl_b64 s[10:11], s[38:39], 19
	s_lshl_b64 s[12:13], s[12:13], 19
	s_add_u32 s42, s49, s12
	s_addc_u32 s43, s50, s13
	s_add_i32 s39, s51, 0
	s_add_i32 m0, s39, 0x10000
	v_lshl_or_b32 v134, v0, 11, v1
	global_load_lds_dwordx4 v130, s[42:43]
	s_add_i32 m0, s39, 0x12000
	s_add_u32 s40, s47, s10
	v_lshl_or_b32 v128, v4, 11, v1
	global_load_lds_dwordx4 v134, s[42:43]
	s_addc_u32 s41, s48, s11
	s_mov_b32 m0, s39
	s_add_i32 s56, s39, 0x2000
	v_lshl_or_b32 v132, v3, 11, v1
	global_load_lds_dwordx4 v128, s[40:41]
	s_mov_b32 m0, s56
	s_add_u32 s10, s42, 0x40000
	global_load_lds_dwordx4 v132, s[40:41]
	s_addc_u32 s11, s43, 0
	s_add_i32 m0, s39, 0x14000
	v_mov_b32_e32 v131, 0
	global_load_lds_dwordx4 v130, s[10:11]
	s_add_i32 m0, s39, 0x16000
	v_mov_b32_e32 v135, v131
	global_load_lds_dwordx4 v134, s[10:11]
	s_add_u32 s10, s40, 0x40000
	s_addc_u32 s11, s41, 0
	s_add_i32 s57, s39, 0x4000
	s_mov_b32 m0, s57
	s_add_i32 s58, s39, 0x6000
	global_load_lds_dwordx4 v128, s[10:11]
	s_mov_b32 m0, s58
	v_mov_b32_e32 v129, v131
	global_load_lds_dwordx4 v132, s[10:11]
	v_mov_b32_e32 v133, v131
	s_mov_b32 s59, 0
	v_lshl_add_u64 v[6:7], s[42:43], 0, v[130:131]
	v_lshl_add_u64 v[4:5], s[42:43], 0, v[134:135]
	v_lshl_add_u64 v[2:3], s[40:41], 0, v[128:129]
	s_cmp_lg_u32 s1, 1
	v_lshl_add_u64 v[0:1], s[40:41], 0, v[132:133]
	s_cbranch_scc1 .LBB0_427
	s_barrier
; #define PG8_STAGE(bufoff, gbase, voff) do { _Pragma("unroll") for (int _i = 0; _i < 2; ++_i) \
;         __builtin_amdgcn_global_load_lds((const unsigned*)((const char*)(gbase) + (voff)[_i]), (LAS unsigned*)(lds + (bufoff) + ldsw + _i * 8192), 16, 0, 0); } while (0)
; #define PG8_WAIT_V(n) asm volatile("s_waitcnt vmcnt(" #n ")" ::: "memory")
; #define PG8_BAR __builtin_amdgcn_s_barrier()
;     __device__ bool next(int i, Unit& u) const {
;         if (rev && i >= rev) return false;
;         const long L = (long)(rev ? rev - 1 - i : i) * G + c; if (L >= nwg) return false;
;         int wgid = (int)L; { const int q = nwg / NXCD, r = nwg % NXCD, xcd = wgid % NXCD, off = wgid / NXCD; wgid = (xcd < r ? xcd * (q + 1) : r * (q + 1) + (xcd - r) * q) + off; }
;         const int nig = WGM * nN, gid = wgid / nig, fm = gid * WGM, gsz = (nM - fm) < WGM ? (nM - fm) : WGM;
;         u.pm = fm + ((wgid % nig) % gsz); u.pn = (wgid % nig) / gsz; return true;
; template <class Epi, class Ptrs>
; __device__ __forceinline__ void gemm_phase(LAS unsigned char* lds, const int K, const StaticOrder& S, const Ptrs& P, const Epi& E) {
;     ...
;     PG8_STAGE(PG8_SB(1, 0), cB + kstep, voffB); PG8_STAGE(PG8_SA(1, 0), cA + kstep, voffA); PG8_STAGE(PG8_SB(1, 1), cB + hstep + kstep, voffB);
;     PG8_WAIT_V(6); PG8_BAR;
;     for (;;) {
;         const bool has_next = S.next(ui + 1, nxt);
.LBB0_427:
	s_nop 0
	s_nop 0
	s_nop 0
	s_nop 0
	s_nop 0
	s_nop 0
	s_nop 0
	s_nop 0
	s_nop 0
	s_nop 0
	s_nop 0
	s_nop 0
	s_nop 0
	s_nop 0
	s_nop 0
	s_nop 0
	s_nop 0
	s_nop 0
	s_nop 0
	s_nop 0
	s_nop 0
	s_nop 0
	s_nop 0
	s_nop 0
	s_nop 0
	s_nop 0
	s_nop 0
	s_nop 0
	s_nop 0
	s_nop 0
	s_nop 0
	s_nop 0
	s_nop 0
	s_nop 0
	s_nop 0
	s_nop 0
	s_nop 0
	s_nop 0
	s_nop 0
	s_nop 0
	s_nop 0
	s_nop 0
	s_nop 0
	s_nop 0
	s_nop 0
	s_nop 0
	s_nop 0
	s_nop 0
	s_nop 0
	s_nop 0
	s_nop 0
	s_nop 0
	s_nop 0
	s_nop 0
	s_nop 0
	s_nop 0
	s_nop 0
	s_nop 0
	s_nop 0
	s_nop 0
	s_add_u32 s10, s28, 0xe000000
	s_addc_u32 s11, s29, 0
	s_lshl_b32 s4, s4, 5
	s_mov_b64 s[12:13], 0x80
	s_and_b32 s15, s4, 0x60
	s_add_i32 m0, s39, 0x18000
	v_lshl_add_u64 v[6:7], v[6:7], 0, s[12:13]
	s_ashr_i32 s60, s3, 31
	s_lshl_b32 s14, s1, 13
	s_lshl_b32 s16, s15, 7
	s_waitcnt vmcnt(4)
	s_barrier
	global_load_lds_dwordx4 v[6:7], off
	v_lshl_add_u64 v[4:5], v[4:5], 0, s[12:13]
	s_add_i32 m0, s39, 0x1a000
	s_add_i32 s61, s39, 0x8000
	s_add_i32 s62, s39, 0xa000
	global_load_lds_dwordx4 v[4:5], off
	v_lshl_add_u64 v[2:3], v[2:3], 0, s[12:13]
	s_mov_b32 m0, s61
	s_add_u32 s4, s42, 0x40080
	global_load_lds_dwordx4 v[2:3], off
	v_lshl_add_u64 v[0:1], v[0:1], 0, s[12:13]
	s_mov_b32 m0, s62
	s_addc_u32 s5, s43, 0
	global_load_lds_dwordx4 v[0:1], off
	s_add_i32 m0, s39, 0x1c000
	v_lshl_add_u64 v[0:1], s[4:5], 0, v[130:131]
	global_load_lds_dwordx4 v[0:1], off
	v_lshl_add_u64 v[0:1], s[4:5], 0, v[134:135]
	s_add_i32 m0, s39, 0x1e000
	s_sext_i32_i8 s69, s0
	global_load_lds_dwordx4 v[0:1], off
	v_and_b32_e32 v0, 15, v208
	v_lshlrev_b32_e32 v1, 1, v11
	v_lshlrev_b32_e32 v2, 6, v208
	s_movk_i32 s0, 0x3c0
	v_lshlrev_b32_e32 v3, 2, v208
	v_and_or_b32 v2, v2, s0, v1
	v_and_b32_e32 v3, 32, v3
	v_lshl_or_b32 v146, s1, 6, v0
	v_lshl_or_b32 v0, v0, 6, v1
	v_lshlrev_b32_e32 v1, 8, v208
	v_bitop3_b32 v147, s16, v2, v3 bitop3:0xf6
	v_and_b32_e32 v1, 0x38000, v1
	v_lshlrev_b32_e32 v2, 11, v10
	v_or3_b32 v1, v8, v1, v2
	v_add_u32_e32 v136, v1, v9
	v_lshlrev_b32_e32 v1, 4, v12
	s_waitcnt vmcnt(6)
	v_and_b32_e32 v1, 0x78000, v1
	v_bitop3_b32 v0, v0, s14, v3 bitop3:0xde
	v_or3_b32 v1, v8, v1, v2
	s_add_i32 s63, 0, 0x10000
	s_add_i32 s64, 0, 0x14000
	v_or_b32_e32 v148, s15, v11
	v_mov_b32_e32 v137, v131
	v_add_u32_e32 v138, v1, v9
	v_mov_b32_e32 v139, v131
	v_mov_b64_e32 v[140:141], 0x1800
	v_mov_b64_e32 v[142:143], 0x17ff
	v_add_u32_e32 v149, s63, v147
	v_add_u32_e32 v150, 0, v0
	v_add_u32_e32 v151, s64, v147
	s_mov_b64 s[14:15], 0x100000
	s_mov_b32 s65, 0x100000
	s_mov_b64 s[16:17], 0x120000
	s_mov_b32 s66, 0x120000
	s_mov_b64 s[18:19], 0x140000
	s_mov_b32 s67, 0x140000
	s_mov_b64 s[20:21], 0x160000
	s_mov_b32 s68, 0x160000
	s_barrier
.LBB0_428:
	s_add_i32 s59, s59, 1
	s_sub_i32 s74, 23, s59
	s_cmpk_eq_i32 s3, 0x100
	s_cselect_b32 s74, s74, s59
	s_mul_i32 s0, s74, s60
	s_mul_hi_u32 s1, s74, s3
	s_add_i32 s1, s1, s0
	s_mul_i32 s0, s74, s3
	s_add_u32 s36, s0, s2
	s_addc_u32 s37, s1, s54
	v_cmp_gt_i64_e64 s[4:5], s[36:37], v[142:143]
	v_cmp_lt_i64_e64 s[0:1], s[36:37], v[140:141]
	s_and_b64 vcc, exec, s[4:5]
	s_cbranch_vccnz .LBB0_430
	s_ashr_i32 s22, s36, 31
	s_lshr_b32 s22, s22, 29
	s_add_i32 s22, s36, s22
	s_ashr_i32 s23, s22, 3
	s_and_b32 s22, s22, -8
	s_sub_i32 s22, s36, s22
	s_cmp_lt_i32 s22, 0
	s_cselect_b32 s24, s55, 0x300
	s_mul_i32 s22, s22, s24
	s_add_i32 s22, s22, s23
	s_ashr_i32 s23, s22, 31
	s_lshr_b32 s23, s23, 25
	s_add_i32 s23, s22, s23
	s_ashr_i32 s24, s23, 7
	s_lshl_b32 s24, s24, 3
	s_sub_i32 s25, 0x180, s24
	s_min_i32 s25, s25, 8
	s_abs_i32 s36, s25
	v_cvt_f32_u32_e32 v0, s36
	s_sub_i32 s44, 0, s36
	s_and_b32 s23, s23, 0xffffff80
	s_sub_i32 s23, s22, s23
	v_rcp_iflag_f32_e32 v0, v0
	s_abs_i32 s22, s23
	s_xor_b32 s37, s23, s25
	s_ashr_i32 s37, s37, 31
	v_mul_f32_e32 v0, 0x4f7ffffe, v0
	v_cvt_u32_f32_e32 v0, v0
	s_nop 0
	v_readfirstlane_b32 s45, v0
	s_mul_i32 s44, s44, s45
	s_mul_hi_u32 s44, s45, s44
	s_add_i32 s45, s45, s44
	s_mul_hi_u32 s44, s22, s45
	s_mul_i32 s45, s44, s36
	s_sub_i32 s22, s22, s45
	s_add_i32 s70, s44, 1
	s_sub_i32 s45, s22, s36
	s_cmp_ge_u32 s22, s36
	s_cselect_b32 s44, s70, s44
	s_cselect_b32 s22, s45, s22
	s_add_i32 s45, s44, 1
	s_cmp_ge_u32 s22, s36
	s_cselect_b32 s22, s45, s44
	s_xor_b32 s22, s22, s37
	s_sub_i32 s22, s22, s37
	s_mul_i32 s25, s22, s25
	s_sub_i32 s23, s23, s25
	s_add_i32 s24, s24, s23

; __device__ __forceinline__ unsigned xb_ld(unsigned* p)              { return __hip_atomic_load(p, __ATOMIC_RELAXED, __HIP_MEMORY_SCOPE_AGENT); }
; __device__ __forceinline__ void xcd_barrier_complete(unsigned* bar, unsigned x, unsigned& nloc, unsigned& nx) {
;     const unsigned G = gridDim.x * gridDim.y * gridDim.z;
;     unsigned sum, cnt, mine, sp = 0u;
;     for (;;) {
;         sum = 0u; cnt = 0u; mine = 0u;
; #pragma unroll
;         for (unsigned j = 0; j < 16; ++j) { const unsigned c = xb_ld(&bar[XB_XCNT(j)]); sum += c; cnt += (c > 0u) ? 1u : 0u; mine = (j == x) ? c : mine; }
; __device__ __forceinline__ void xcd_barrier(const XcdBarrier& b) {
;     asm volatile("s_waitcnt vmcnt(0)" ::: "memory");
;     __syncthreads();
;     if (threadIdx.x == 0) {
;         unsigned* bar = b.bar;
;         __builtin_amdgcn_s_waitcnt(0);
;         unsigned nloc = b.st[0], nx = b.st[1];
;         if (nloc == 0u) { xcd_barrier_complete(bar, b.x, nloc, nx); b.st[0] = nloc; b.st[1] = nx; }
.LBB0_438:
	s_nop 0
	s_nop 0
	s_nop 0
	s_nop 0
	s_nop 0
	s_nop 0
	s_nop 0
	s_nop 0
	s_nop 0
	s_nop 0
	s_nop 0
	s_nop 0
	s_nop 0
	s_nop 0
	s_nop 0
	s_nop 0
	s_nop 0
	s_nop 0
	s_nop 0
	s_nop 0
	s_nop 0
	s_nop 0
	s_nop 0
	s_nop 0
	s_nop 0
	s_nop 0
	s_nop 0
	s_nop 0
	s_nop 0
	s_nop 0
	s_nop 0
	s_nop 0
	s_nop 0
	s_nop 0
	s_nop 0
	s_nop 0
	s_nop 0
	s_nop 0
	s_nop 0
	s_nop 0
	s_nop 0
	s_nop 0
	s_nop 0
	s_nop 0
	s_nop 0
	s_nop 0
	s_nop 0
	s_nop 0
	s_nop 0
	s_nop 0
	s_nop 0
	s_nop 0
	s_nop 0
	s_nop 0
	s_nop 0
	s_nop 0
	s_nop 0
	s_nop 0
	s_nop 0
	s_nop 0
	s_nop 0
	s_cmp_gt_i32 s31, 5
	s_cselect_b64 s[0:1], -1, 0
	s_and_b64 s[4:5], s[6:7], s[0:1]
	s_andn2_b64 vcc, exec, s[4:5]
	s_cbranch_vccnz .LBB0_488
	s_waitcnt vmcnt(0)
	s_waitcnt vmcnt(0) lgkmcnt(0)
	s_barrier
	s_and_saveexec_b64 s[4:5], s[8:9]
	s_cbranch_execz .LBB0_487
	s_add_i32 s6, 0, 0x25ff0
	v_mov_b32_e32 v0, s6
	s_waitcnt vmcnt(0) expcnt(0) lgkmcnt(0)
	ds_read_b32 v2, v0
	s_add_i32 s6, 0, 0x25ff4
	v_mov_b32_e32 v0, s6
	ds_read_b32 v0, v0
	s_waitcnt lgkmcnt(1)
	v_cmp_ne_u32_e32 vcc, 0, v2
	s_cbranch_vccnz .LBB0_455
	s_load_dwordx2 s[10:11], s[52:53], 0x4
	s_add_u32 s6, s28, 0x3e800200
	s_addc_u32 s7, s29, 0
	s_add_u32 s8, s28, 0x3e800400
	s_addc_u32 s9, s29, 0
	s_waitcnt lgkmcnt(0)
	s_mul_i32 s31, s10, s3
	s_add_u32 s10, s28, 0x3e800500
	s_mul_i32 s31, s31, s11
	s_addc_u32 s11, s29, 0
	s_add_u32 s12, s28, 0x3e800600
	s_addc_u32 s13, s29, 0
	s_add_u32 s14, s28, 0x3e800700
	s_addc_u32 s15, s29, 0
	s_add_u32 s16, s28, 0x3e800800
	s_addc_u32 s17, s29, 0
	s_add_u32 s18, s28, 0x3e800900
	s_addc_u32 s19, s29, 0
	s_add_u32 s20, s28, 0x3e800a00
	s_addc_u32 s21, s29, 0
	s_add_u32 s22, s28, 0x3e800b00
	s_addc_u32 s23, s29, 0
	s_add_u32 s24, s28, 0x3e800c00
	s_addc_u32 s25, s29, 0
	s_add_u32 s36, s28, 0x3e800d00
	s_addc_u32 s37, s29, 0
	s_add_u32 s38, s28, 0x3e800e00
	s_addc_u32 s39, s29, 0
	s_add_u32 s40, s28, 0x3e800f00
	s_addc_u32 s41, s29, 0
	s_add_u32 s42, s28, 0x3e801000
	s_addc_u32 s43, s29, 0
	s_add_u32 s44, s28, 0x3e801100
	s_addc_u32 s45, s29, 0
	s_add_u32 s46, s28, 0x3e801200
	s_addc_u32 s47, s29, 0
	s_add_u32 s48, s28, 0x3e801300
	s_addc_u32 s49, s29, 0
	s_mov_b32 s56, 1
	v_mov_b32_e32 v16, 0
	s_branch .LBB0_443
